# attention loop: counted vmcnt waits - the mid-trip stage write no longer drains the tile loads issued at the top of the same trip (vmcnt(5) instead of vmcnt(1)/(0)); the end-of-trip write waits vmcnt(
# speedup vs baseline: 1.0020x; 1.0020x over previous
; #define MFMA(a, b, c) __builtin_amdgcn_mfma_f32_32x32x16_bf16((a), (b), (c), 0, 0, 0)
; DI float fexp2(float x) { return __builtin_amdgcn_exp2f(x); }
; DI void phase_attn(const Params& p, int hf, bool skipctx, char* smem, int& rot) {
;     ...
;         for (int ks = 0; ks < 6; ++ks)
; #pragma unroll
;           for (int kb = 0; kb < 2; ++kb) st[kb] = MFMA(kf[kb][ks], qf[ks], st[kb]);
;         __builtin_amdgcn_sched_barrier(0);
;       }
;       bf16x8 vf[2][2][2];
; #pragma unroll
;       for (int kb = 0; kb < 2; ++kb)
; #pragma unroll
;         for (int s2 = 0; s2 < 2; ++s2)
; #pragma unroll
;           for (int dvb = 0; dvb < 2; ++dvb) {
;             const char* vp = sv + (dvb * 32 + r) * VROW + (kb * 32 + 16 * s2 + 4 * h) * 2;
;             const s16x4 lo = *(const s16x4*)vp, hi = *(const s16x4*)(vp + 16);
;             vf[kb][s2][dvb] = __builtin_shufflevector(lo, hi, 0, 1, 2, 3, 4, 5, 6, 7);
;           }
;       float mx = st[0][0];
; #pragma unroll
;       for (int i = 0; i < 16; ++i) { mx = fmaxf(mx, st[0][i]); mx = fmaxf(mx, st[1][i]); }
;       if (__any(mx > m_run + 8.f)) {
;         mx = fmaxf(mx, __shfl_xor(mx, 32));
;         const float m_new = fmaxf(m_run, mx);
;         const float alpha = fexp2(m_run - m_new);
;         m_run = m_new;
;         l_run *= alpha;
; #pragma unroll
;         for (int i = 0; i < 16; ++i) { o[0][i] *= alpha; o[1][i] *= alpha; }
;       }
;       float ps = 0.f;
; #pragma unroll
;       for (int kb = 0; kb < 2; ++kb)
; #pragma unroll
;         for (int i = 0; i < 16; ++i) { const float e = fexp2(st[kb][i] - m_run); st[kb][i] = e; ps += e; }
;       l_run += ps;
; #pragma unroll
;       for (int kb = 0; kb < 2; ++kb)
; #pragma unroll
;         for (int s2 = 0; s2 < 2; ++s2) {
;           const bf16x8 pb = pack8(st[kb][8 * s2 + 0], st[kb][8 * s2 + 1], st[kb][8 * s2 + 2], st[kb][8 * s2 + 3], st[kb][8 * s2 + 4], st[kb][8 * s2 + 5], st[kb][8 * s2 + 6], st[kb][8 * s2 + 7]);
; #pragma unroll
;           for (int dvb = 0; dvb < 2; ++dvb) o[dvb] = MFMA(vf[kb][s2][dvb], pb, o[dvb]);
;     ...
;       if (kt + 2 < nkt) ATT_LOAD(ak0, ak1, ak2, av0, av1, kt + 2);
;       compute(0, 0); compute(0, 1);
;       ATT_WRITE(bk0, bk1, bk2, bv0, bv1, 1);
;       __syncthreads();
;       if (kt + 3 < nkt) ATT_LOAD(bk0, bk1, bk2, bv0, bv1, kt + 3);
.Lsc0_mj0:
	s_waitcnt lgkmcnt(11)
	v_mfma_f32_32x32x16_bf16 v[48:63], v[36:39], v[64:67], v[176:191]
	s_waitcnt lgkmcnt(5)
	v_mfma_f32_32x32x16_bf16 v[32:47], v[40:43], v[64:67], v[176:191]
	v_mfma_f32_32x32x16_bf16 v[48:63], v[132:135], v[68:71], v[48:63]
	s_waitcnt lgkmcnt(4)
	v_mfma_f32_32x32x16_bf16 v[32:47], v[152:155], v[68:71], v[32:47]
	v_mfma_f32_32x32x16_bf16 v[48:63], v[136:139], v[72:75], v[48:63]
	s_waitcnt lgkmcnt(3)
	v_mfma_f32_32x32x16_bf16 v[32:47], v[156:159], v[72:75], v[32:47]
	v_mfma_f32_32x32x16_bf16 v[48:63], v[140:143], v[88:91], v[48:63]
	s_waitcnt lgkmcnt(2)
	v_mfma_f32_32x32x16_bf16 v[32:47], v[234:237], v[88:91], v[32:47]
	v_mfma_f32_32x32x16_bf16 v[48:63], v[144:147], v[96:99], v[48:63]
	s_waitcnt lgkmcnt(1)
	v_mfma_f32_32x32x16_bf16 v[32:47], v[238:241], v[96:99], v[32:47]
	v_mfma_f32_32x32x16_bf16 v[48:63], v[148:151], v[100:103], v[48:63]
	s_waitcnt lgkmcnt(0)
	v_mfma_f32_32x32x16_bf16 v[32:47], v[242:245], v[100:103], v[32:47]
	s_nop 3
	ds_read_b128 v[156:159], v211 offset:128
	ds_read_b128 v[148:151], v211 offset:160
	ds_read_b128 v[152:155], v211 offset:8832
	ds_read_b128 v[144:147], v211 offset:8864
	ds_read_b128 v[140:143], v211 offset:192
	ds_read_b128 v[136:139], v211 offset:8896
	ds_read_b128 v[128:131], v211 offset:224
	ds_read_b128 v[132:135], v211 offset:8928
	v_exp_f32_e32 v48, v48
	v_exp_f32_e32 v49, v49
	v_exp_f32_e32 v50, v50
	v_exp_f32_e32 v51, v51
	v_exp_f32_e32 v52, v52
	v_exp_f32_e32 v53, v53
	v_exp_f32_e32 v54, v54
	v_exp_f32_e32 v55, v55
	v_exp_f32_e32 v56, v56
	v_exp_f32_e32 v57, v57
	v_exp_f32_e32 v58, v58
	v_exp_f32_e32 v59, v59
	v_exp_f32_e32 v60, v60
	v_exp_f32_e32 v61, v61
	v_exp_f32_e32 v62, v62
	v_exp_f32_e32 v63, v63
	v_exp_f32_e32 v32, v32
	v_exp_f32_e32 v33, v33
	v_exp_f32_e32 v34, v34
	v_exp_f32_e32 v35, v35
	v_exp_f32_e32 v36, v36
	v_exp_f32_e32 v37, v37
	v_exp_f32_e32 v38, v38
	v_exp_f32_e32 v39, v39
	v_exp_f32_e32 v40, v40
	v_exp_f32_e32 v41, v41
	v_exp_f32_e32 v42, v42
	v_exp_f32_e32 v43, v43
	v_exp_f32_e32 v44, v44
	v_exp_f32_e32 v45, v45
	v_exp_f32_e32 v46, v46
	v_exp_f32_e32 v47, v47
	v_add_f32_e32 v195, v48, v49
	v_add_f32_e32 v195, v195, v50
	v_add_f32_e32 v195, v195, v51
	v_add_f32_e32 v195, v195, v52
	v_add_f32_e32 v195, v195, v53
	v_add_f32_e32 v195, v195, v54
	v_add_f32_e32 v195, v195, v55
	v_add_f32_e32 v195, v195, v56
	v_add_f32_e32 v195, v195, v57
	v_add_f32_e32 v195, v195, v58
	v_add_f32_e32 v195, v195, v59
	v_add_f32_e32 v195, v195, v60
	v_add_f32_e32 v195, v195, v61
	v_add_f32_e32 v195, v195, v62
	v_add_f32_e32 v195, v195, v63
	v_add_f32_e32 v195, v195, v32
	v_add_f32_e32 v195, v195, v33
	v_add_f32_e32 v195, v195, v34
	v_add_f32_e32 v195, v195, v35
	v_add_f32_e32 v195, v195, v36
	v_add_f32_e32 v195, v195, v37
	v_add_f32_e32 v195, v195, v38
	v_add_f32_e32 v195, v195, v39
	v_add_f32_e32 v195, v195, v40
	v_add_f32_e32 v195, v195, v41
	v_add_f32_e32 v195, v195, v42
	v_add_f32_e32 v195, v195, v43
	v_add_f32_e32 v195, v195, v44
	v_add_f32_e32 v195, v195, v45
	v_add_f32_e32 v195, v195, v46
	v_add_f32_e32 v195, v195, v47
	v_cmp_nle_f32_e32 vcc, v195, v167
	s_cbranch_vccnz .Lsc0_fb1
	v_add_f32_e32 v213, v213, v195
	v_cvt_pk_bf16_f32 v48, v48, v49
	v_cvt_pk_bf16_f32 v49, v50, v51
	v_cvt_pk_bf16_f32 v50, v52, v53
	v_cvt_pk_bf16_f32 v51, v54, v55
	v_cvt_pk_bf16_f32 v52, v56, v57
	v_cvt_pk_bf16_f32 v53, v58, v59
	v_cvt_pk_bf16_f32 v54, v60, v61
	v_cvt_pk_bf16_f32 v55, v62, v63
	v_cvt_pk_bf16_f32 v56, v32, v33
	v_cvt_pk_bf16_f32 v57, v34, v35
	v_cvt_pk_bf16_f32 v58, v36, v37
	v_cvt_pk_bf16_f32 v59, v38, v39
	v_cvt_pk_bf16_f32 v60, v40, v41
	v_cvt_pk_bf16_f32 v61, v42, v43
	v_cvt_pk_bf16_f32 v62, v44, v45
	v_cvt_pk_bf16_f32 v63, v46, v47
	s_waitcnt lgkmcnt(7)
	s_nop 0
	v_mfma_f32_32x32x16_bf16 v[16:31], v[156:159], v[48:51], v[16:31]
	s_waitcnt lgkmcnt(5)
	v_mfma_f32_32x32x16_bf16 v[0:15], v[152:155], v[48:51], v[0:15]
	s_nop 1
	v_mfma_f32_32x32x16_bf16 v[16:31], v[148:151], v[52:55], v[16:31]
	s_waitcnt lgkmcnt(4)
	v_mfma_f32_32x32x16_bf16 v[0:15], v[144:147], v[52:55], v[0:15]
	s_waitcnt lgkmcnt(3)
	s_nop 0
	v_mfma_f32_32x32x16_bf16 v[16:31], v[140:143], v[56:59], v[16:31]
	s_waitcnt lgkmcnt(2)
	v_mfma_f32_32x32x16_bf16 v[0:15], v[136:139], v[56:59], v[0:15]
	s_add_i32 s4, s4, 3
	s_cmp_ge_u32 s4, s13
	s_waitcnt lgkmcnt(1)
	v_mfma_f32_32x32x16_bf16 v[16:31], v[128:131], v[60:63], v[16:31]
	s_mov_b64 vcc, s[26:27]
	s_cbranch_vccnz .Lvmw_l1
	s_waitcnt vmcnt(5)
	s_branch .Lvmw_g1

; DI void phase_attn(const Params& p, int hf, bool skipctx, char* smem, int& rot) {
;     ...
;       ATT_WRITE(bk0, bk1, bk2, bv0, bv1, 1);
;       __syncthreads();
;       if (kt + 3 < nkt) ATT_LOAD(bk0, bk1, bk2, bv0, bv1, kt + 3);
;       compute(1, 0); compute(1, 1);
;       if (kt + 2 < nkt) ATT_WRITE(ak0, ak1, ak2, av0, av1, 0);
;       __syncthreads();
;     }
.Lvmw_g1:
	ds_write_b128 v194, v[112:115] offset:44032
	ds_write_b128 v204, v[108:111] offset:44032
	ds_write_b128 v206, v[116:119] offset:44032
	ds_write_b64 v208, v[120:121] offset:44032
	ds_write_b64 v208, v[122:123] offset:44048
	ds_write_b64 v208, v[124:125] offset:52736
	ds_write_b64 v208, v[126:127] offset:52752
	s_waitcnt lgkmcnt(0)
	s_barrier
	v_mfma_f32_32x32x16_bf16 v[0:15], v[132:135], v[60:63], v[0:15]
	s_cbranch_scc1 .LBB0_803
	v_add_u32_e32 v200, 0x6000, v174
	v_add_u32_e32 v201, 0x6000, v172
	v_add_u32_e32 v202, 0x6000, v170
	global_load_dwordx4 v[112:115], v200, s[94:95]
	global_load_dwordx4 v[108:111], v201, s[94:95]
	global_load_dwordx4 v[116:119], v202, s[94:95]
	global_load_dwordx4 v[120:123], v166, s[94:95]
	global_load_dwordx4 v[124:127], v168, s[94:95]

; #define MFMA(a, b, c) __builtin_amdgcn_mfma_f32_32x32x16_bf16((a), (b), (c), 0, 0, 0)
; DI float fexp2(float x) { return __builtin_amdgcn_exp2f(x); }
; DI void phase_attn(const Params& p, int hf, bool skipctx, char* smem, int& rot) {
;     ...
;         for (int ks = 0; ks < 6; ++ks)
; #pragma unroll
;           for (int kb = 0; kb < 2; ++kb) st[kb] = MFMA(kf[kb][ks], qf[ks], st[kb]);
;         __builtin_amdgcn_sched_barrier(0);
;       }
;       bf16x8 vf[2][2][2];
; #pragma unroll
;       for (int kb = 0; kb < 2; ++kb)
; #pragma unroll
;         for (int s2 = 0; s2 < 2; ++s2)
; #pragma unroll
;           for (int dvb = 0; dvb < 2; ++dvb) {
;             const char* vp = sv + (dvb * 32 + r) * VROW + (kb * 32 + 16 * s2 + 4 * h) * 2;
;             const s16x4 lo = *(const s16x4*)vp, hi = *(const s16x4*)(vp + 16);
;             vf[kb][s2][dvb] = __builtin_shufflevector(lo, hi, 0, 1, 2, 3, 4, 5, 6, 7);
;           }
;       float mx = st[0][0];
; #pragma unroll
;       for (int i = 0; i < 16; ++i) { mx = fmaxf(mx, st[0][i]); mx = fmaxf(mx, st[1][i]); }
;       if (__any(mx > m_run + 8.f)) {
;         mx = fmaxf(mx, __shfl_xor(mx, 32));
;         const float m_new = fmaxf(m_run, mx);
;         const float alpha = fexp2(m_run - m_new);
;         m_run = m_new;
;         l_run *= alpha;
; #pragma unroll
;         for (int i = 0; i < 16; ++i) { o[0][i] *= alpha; o[1][i] *= alpha; }
;       }
;       float ps = 0.f;
; #pragma unroll
;       for (int kb = 0; kb < 2; ++kb)
; #pragma unroll
;         for (int i = 0; i < 16; ++i) { const float e = fexp2(st[kb][i] - m_run); st[kb][i] = e; ps += e; }
;       l_run += ps;
; #pragma unroll
;       for (int kb = 0; kb < 2; ++kb)
; #pragma unroll
;         for (int s2 = 0; s2 < 2; ++s2) {
;           const bf16x8 pb = pack8(st[kb][8 * s2 + 0], st[kb][8 * s2 + 1], st[kb][8 * s2 + 2], st[kb][8 * s2 + 3], st[kb][8 * s2 + 4], st[kb][8 * s2 + 5], st[kb][8 * s2 + 6], st[kb][8 * s2 + 7]);
; #pragma unroll
;           for (int dvb = 0; dvb < 2; ++dvb) o[dvb] = MFMA(vf[kb][s2][dvb], pb, o[dvb]);
;     ...
;       compute(1, 0); compute(1, 1);
;       if (kt + 2 < nkt) ATT_WRITE(ak0, ak1, ak2, av0, av1, 0);
.Lsc0_mj2:
	s_waitcnt lgkmcnt(11)
	v_mfma_f32_32x32x16_bf16 v[48:63], v[36:39], v[64:67], v[176:191]
	s_waitcnt lgkmcnt(5)
	v_mfma_f32_32x32x16_bf16 v[32:47], v[40:43], v[64:67], v[176:191]
	v_mfma_f32_32x32x16_bf16 v[48:63], v[132:135], v[68:71], v[48:63]
	s_waitcnt lgkmcnt(4)
	v_mfma_f32_32x32x16_bf16 v[32:47], v[152:155], v[68:71], v[32:47]
	v_mfma_f32_32x32x16_bf16 v[48:63], v[136:139], v[72:75], v[48:63]
	s_waitcnt lgkmcnt(3)
	v_mfma_f32_32x32x16_bf16 v[32:47], v[156:159], v[72:75], v[32:47]
	v_mfma_f32_32x32x16_bf16 v[48:63], v[140:143], v[88:91], v[48:63]
	s_waitcnt lgkmcnt(2)
	v_mfma_f32_32x32x16_bf16 v[32:47], v[216:219], v[88:91], v[32:47]
	v_mfma_f32_32x32x16_bf16 v[48:63], v[144:147], v[96:99], v[48:63]
	s_waitcnt lgkmcnt(1)
	v_mfma_f32_32x32x16_bf16 v[32:47], v[234:237], v[96:99], v[32:47]
	v_mfma_f32_32x32x16_bf16 v[48:63], v[148:151], v[100:103], v[48:63]
	s_waitcnt lgkmcnt(0)
	v_mfma_f32_32x32x16_bf16 v[32:47], v[238:241], v[100:103], v[32:47]
	s_nop 3
	ds_read_b128 v[152:155], v211 offset:52864
	ds_read_b128 v[156:159], v211 offset:44160
	ds_read_b128 v[148:151], v211 offset:44192
	ds_read_b128 v[144:147], v211 offset:52896
	ds_read_b128 v[140:143], v211 offset:44224
	ds_read_b128 v[136:139], v211 offset:52928
	ds_read_b128 v[132:135], v211 offset:44256
	ds_read_b128 v[128:131], v211 offset:52960
	v_exp_f32_e32 v48, v48
	v_exp_f32_e32 v49, v49
	v_exp_f32_e32 v50, v50
	v_exp_f32_e32 v51, v51
	v_exp_f32_e32 v52, v52
	v_exp_f32_e32 v53, v53
	v_exp_f32_e32 v54, v54
	v_exp_f32_e32 v55, v55
	v_exp_f32_e32 v56, v56
	v_exp_f32_e32 v57, v57
	v_exp_f32_e32 v58, v58
	v_exp_f32_e32 v59, v59
	v_exp_f32_e32 v60, v60
	v_exp_f32_e32 v61, v61
	v_exp_f32_e32 v62, v62
	v_exp_f32_e32 v63, v63
	v_exp_f32_e32 v32, v32
	v_exp_f32_e32 v33, v33
	v_exp_f32_e32 v34, v34
	v_exp_f32_e32 v35, v35
	v_exp_f32_e32 v36, v36
	v_exp_f32_e32 v37, v37
	v_exp_f32_e32 v38, v38
	v_exp_f32_e32 v39, v39
	v_exp_f32_e32 v40, v40
	v_exp_f32_e32 v41, v41
	v_exp_f32_e32 v42, v42
	v_exp_f32_e32 v43, v43
	v_exp_f32_e32 v44, v44
	v_exp_f32_e32 v45, v45
	v_exp_f32_e32 v46, v46
	v_exp_f32_e32 v47, v47
	v_add_f32_e32 v195, v48, v49
	v_add_f32_e32 v195, v195, v50
	v_add_f32_e32 v195, v195, v51
	v_add_f32_e32 v195, v195, v52
	v_add_f32_e32 v195, v195, v53
	v_add_f32_e32 v195, v195, v54
	v_add_f32_e32 v195, v195, v55
	v_add_f32_e32 v195, v195, v56
	v_add_f32_e32 v195, v195, v57
	v_add_f32_e32 v195, v195, v58
	v_add_f32_e32 v195, v195, v59
	v_add_f32_e32 v195, v195, v60
	v_add_f32_e32 v195, v195, v61
	v_add_f32_e32 v195, v195, v62
	v_add_f32_e32 v195, v195, v63
	v_add_f32_e32 v195, v195, v32
	v_add_f32_e32 v195, v195, v33
	v_add_f32_e32 v195, v195, v34
	v_add_f32_e32 v195, v195, v35
	v_add_f32_e32 v195, v195, v36
	v_add_f32_e32 v195, v195, v37
	v_add_f32_e32 v195, v195, v38
	v_add_f32_e32 v195, v195, v39
	v_add_f32_e32 v195, v195, v40
	v_add_f32_e32 v195, v195, v41
	v_add_f32_e32 v195, v195, v42
	v_add_f32_e32 v195, v195, v43
	v_add_f32_e32 v195, v195, v44
	v_add_f32_e32 v195, v195, v45
	v_add_f32_e32 v195, v195, v46
	v_add_f32_e32 v195, v195, v47
	v_cmp_nle_f32_e32 vcc, v195, v167
	s_cbranch_vccnz .Lsc0_fb3
	v_add_f32_e32 v213, v213, v195
	v_cvt_pk_bf16_f32 v48, v48, v49
	v_cvt_pk_bf16_f32 v49, v50, v51
	v_cvt_pk_bf16_f32 v50, v52, v53
	v_cvt_pk_bf16_f32 v51, v54, v55
	v_cvt_pk_bf16_f32 v52, v56, v57
	v_cvt_pk_bf16_f32 v53, v58, v59
	v_cvt_pk_bf16_f32 v54, v60, v61
	v_cvt_pk_bf16_f32 v55, v62, v63
	v_cvt_pk_bf16_f32 v56, v32, v33
	v_cvt_pk_bf16_f32 v57, v34, v35
	v_cvt_pk_bf16_f32 v58, v36, v37
	v_cvt_pk_bf16_f32 v59, v38, v39
	v_cvt_pk_bf16_f32 v60, v40, v41
	v_cvt_pk_bf16_f32 v61, v42, v43
	v_cvt_pk_bf16_f32 v62, v44, v45
	v_cvt_pk_bf16_f32 v63, v46, v47
	s_waitcnt lgkmcnt(6)
	s_nop 0
	v_mfma_f32_32x32x16_bf16 v[16:31], v[156:159], v[48:51], v[16:31]
	v_mfma_f32_32x32x16_bf16 v[0:15], v[152:155], v[48:51], v[0:15]
	s_waitcnt lgkmcnt(5)
	s_nop 0
	v_mfma_f32_32x32x16_bf16 v[16:31], v[148:151], v[52:55], v[16:31]
	s_waitcnt lgkmcnt(4)
	v_mfma_f32_32x32x16_bf16 v[0:15], v[144:147], v[52:55], v[0:15]
	s_waitcnt lgkmcnt(3)
	s_nop 0
	v_mfma_f32_32x32x16_bf16 v[16:31], v[140:143], v[56:59], v[16:31]
	s_waitcnt lgkmcnt(2)
	v_mfma_f32_32x32x16_bf16 v[0:15], v[136:139], v[56:59], v[0:15]
	s_andn2_b64 vcc, exec, s[36:37]
	s_waitcnt lgkmcnt(1)
	v_mfma_f32_32x32x16_bf16 v[16:31], v[132:135], v[60:63], v[16:31]
	s_waitcnt lgkmcnt(0)
	v_mfma_f32_32x32x16_bf16 v[0:15], v[128:131], v[60:63], v[0:15]
	s_cbranch_vccnz .LBB0_809
	s_waitcnt vmcnt(5)
	ds_write_b128 v194, v[76:79]
	ds_write_b128 v204, v[80:83]
	ds_write_b128 v206, v[84:87]
	ds_write_b64 v208, v[92:93] offset:0
	ds_write_b64 v208, v[94:95] offset:16
	ds_write_b64 v208, v[104:105] offset:8704
	ds_write_b64 v208, v[106:107] offset:8720

; #define MFMA(a, b, c) __builtin_amdgcn_mfma_f32_32x32x16_bf16((a), (b), (c), 0, 0, 0)
; DI float fexp2(float x) { return __builtin_amdgcn_exp2f(x); }
; DI void phase_attn(const Params& p, int hf, bool skipctx, char* smem, int& rot) {
;     ...
;         for (int i = 0; i < 16; ++i) { const float e = fexp2(st[kb][i] - m_run); st[kb][i] = e; ps += e; }
;       l_run += ps;
; #pragma unroll
;       for (int kb = 0; kb < 2; ++kb)
; #pragma unroll
;         for (int s2 = 0; s2 < 2; ++s2) {
;           const bf16x8 pb = pack8(st[kb][8 * s2 + 0], st[kb][8 * s2 + 1], st[kb][8 * s2 + 2], st[kb][8 * s2 + 3], st[kb][8 * s2 + 4], st[kb][8 * s2 + 5], st[kb][8 * s2 + 6], st[kb][8 * s2 + 7]);
; #pragma unroll
;           for (int dvb = 0; dvb < 2; ++dvb) o[dvb] = MFMA(vf[kb][s2][dvb], pb, o[dvb]);
;         }
;     ...
;       ATT_WRITE(bk0, bk1, bk2, bv0, bv1, 1);
;       __syncthreads();
;       if (kt + 3 < nkt) ATT_LOAD(bk0, bk1, bk2, bv0, bv1, kt + 3);
.Lsc0_c1_LBB0_801:
	v_exp_f32_e32 v48, v48
	v_exp_f32_e32 v49, v49
	v_exp_f32_e32 v50, v50
	v_exp_f32_e32 v51, v51
	v_exp_f32_e32 v52, v52
	v_exp_f32_e32 v53, v53
	v_exp_f32_e32 v54, v54
	v_exp_f32_e32 v55, v55
	v_cvt_pk_bf16_f32 v214, v48, v49
	v_cvt_pk_bf16_f32 v215, v50, v51
	v_cvt_pk_bf16_f32 v216, v52, v53
	v_cvt_pk_bf16_f32 v217, v54, v55
	s_waitcnt lgkmcnt(7)
	s_nop 0
	v_mfma_f32_32x32x16_bf16 v[16:31], v[156:159], v[214:217], v[16:31]
	v_exp_f32_e32 v56, v56
	s_waitcnt lgkmcnt(5)
	v_mfma_f32_32x32x16_bf16 v[0:15], v[152:155], v[214:217], v[0:15]
	v_exp_f32_e32 v57, v57
	v_exp_f32_e32 v58, v58
	v_exp_f32_e32 v59, v59
	v_exp_f32_e32 v60, v60
	v_exp_f32_e32 v61, v61
	v_exp_f32_e32 v62, v62
	v_exp_f32_e32 v63, v63
	v_cvt_pk_bf16_f32 v152, v56, v57
	v_cvt_pk_bf16_f32 v153, v58, v59
	v_cvt_pk_bf16_f32 v154, v60, v61
	v_cvt_pk_bf16_f32 v155, v62, v63
	s_nop 1
	v_mfma_f32_32x32x16_bf16 v[16:31], v[148:151], v[152:155], v[16:31]
	v_exp_f32_e32 v32, v32
	s_waitcnt lgkmcnt(4)
	v_mfma_f32_32x32x16_bf16 v[0:15], v[144:147], v[152:155], v[0:15]
	v_exp_f32_e32 v33, v33
	v_exp_f32_e32 v34, v34
	v_exp_f32_e32 v35, v35
	v_exp_f32_e32 v36, v36
	v_exp_f32_e32 v37, v37
	v_exp_f32_e32 v38, v38
	v_exp_f32_e32 v39, v39
	v_cvt_pk_bf16_f32 v144, v32, v33
	v_cvt_pk_bf16_f32 v145, v34, v35
	v_cvt_pk_bf16_f32 v146, v36, v37
	v_cvt_pk_bf16_f32 v147, v38, v39
	s_waitcnt lgkmcnt(3)
	s_nop 0
	v_mfma_f32_32x32x16_bf16 v[16:31], v[140:143], v[144:147], v[16:31]
	v_exp_f32_e32 v40, v40
	s_waitcnt lgkmcnt(2)
	v_mfma_f32_32x32x16_bf16 v[0:15], v[136:139], v[144:147], v[0:15]
	v_exp_f32_e32 v41, v41
	v_exp_f32_e32 v42, v42
	v_exp_f32_e32 v43, v43
	v_exp_f32_e32 v44, v44
	v_exp_f32_e32 v45, v45
	v_exp_f32_e32 v46, v46
	v_exp_f32_e32 v47, v47
	v_cvt_pk_bf16_f32 v136, v40, v41
	v_cvt_pk_bf16_f32 v137, v42, v43
	v_cvt_pk_bf16_f32 v138, v44, v45
	v_cvt_pk_bf16_f32 v139, v46, v47
	s_add_i32 s4, s4, 3
	s_cmp_ge_u32 s4, s13
	s_waitcnt lgkmcnt(1)
	v_mfma_f32_32x32x16_bf16 v[16:31], v[128:131], v[136:139], v[16:31]
	s_mov_b64 vcc, s[26:27]
	s_cbranch_vccnz .Lvmw_l2
	s_waitcnt vmcnt(5)
	s_branch .Lvmw_g2

; DI void phase_attn(const Params& p, int hf, bool skipctx, char* smem, int& rot) {
;     ...
;       ATT_WRITE(bk0, bk1, bk2, bv0, bv1, 1);
;       __syncthreads();
;       if (kt + 3 < nkt) ATT_LOAD(bk0, bk1, bk2, bv0, bv1, kt + 3);
;       compute(1, 0); compute(1, 1);
;       if (kt + 2 < nkt) ATT_WRITE(ak0, ak1, ak2, av0, av1, 0);
;       __syncthreads();
;     }
.Lvmw_g2:
	ds_write_b128 v194, v[112:115] offset:44032
	ds_write_b128 v204, v[108:111] offset:44032
	ds_write_b128 v206, v[116:119] offset:44032
	ds_write_b64 v208, v[120:121] offset:44032
	ds_write_b64 v208, v[122:123] offset:44048
	ds_write_b64 v208, v[124:125] offset:52736
	ds_write_b64 v208, v[126:127] offset:52752
	s_waitcnt lgkmcnt(0)
	s_barrier
	v_mfma_f32_32x32x16_bf16 v[0:15], v[132:135], v[136:139], v[0:15]
	s_cbranch_scc1 .Lsc0_c1_LBB0_803
	v_add_u32_e32 v200, 0x6000, v174
	v_add_u32_e32 v201, 0x6000, v172
	v_add_u32_e32 v202, 0x6000, v170
	global_load_dwordx4 v[112:115], v200, s[94:95]
	global_load_dwordx4 v[108:111], v201, s[94:95]
	global_load_dwordx4 v[116:119], v202, s[94:95]
	global_load_dwordx4 v[120:123], v166, s[94:95]
	global_load_dwordx4 v[124:127], v168, s[94:95]

; #define MFMA(a, b, c) __builtin_amdgcn_mfma_f32_32x32x16_bf16((a), (b), (c), 0, 0, 0)
; DI float fexp2(float x) { return __builtin_amdgcn_exp2f(x); }
; DI void phase_attn(const Params& p, int hf, bool skipctx, char* smem, int& rot) {
;     ...
;         for (int i = 0; i < 16; ++i) { const float e = fexp2(st[kb][i] - m_run); st[kb][i] = e; ps += e; }
;       l_run += ps;
; #pragma unroll
;       for (int kb = 0; kb < 2; ++kb)
; #pragma unroll
;         for (int s2 = 0; s2 < 2; ++s2) {
;           const bf16x8 pb = pack8(st[kb][8 * s2 + 0], st[kb][8 * s2 + 1], st[kb][8 * s2 + 2], st[kb][8 * s2 + 3], st[kb][8 * s2 + 4], st[kb][8 * s2 + 5], st[kb][8 * s2 + 6], st[kb][8 * s2 + 7]);
; #pragma unroll
;           for (int dvb = 0; dvb < 2; ++dvb) o[dvb] = MFMA(vf[kb][s2][dvb], pb, o[dvb]);
;         }
;     ...
;       compute(1, 0); compute(1, 1);
;       if (kt + 2 < nkt) ATT_WRITE(ak0, ak1, ak2, av0, av1, 0);
.Lsc0_c3_LBB0_807:
	v_exp_f32_e32 v48, v48
	v_exp_f32_e32 v49, v49
	v_exp_f32_e32 v50, v50
	v_exp_f32_e32 v51, v51
	v_exp_f32_e32 v52, v52
	v_exp_f32_e32 v53, v53
	v_exp_f32_e32 v54, v54
	v_exp_f32_e32 v55, v55
	v_cvt_pk_bf16_f32 v214, v48, v49
	v_cvt_pk_bf16_f32 v215, v50, v51
	v_cvt_pk_bf16_f32 v216, v52, v53
	v_cvt_pk_bf16_f32 v217, v54, v55
	s_waitcnt lgkmcnt(6)
	s_nop 0
	v_mfma_f32_32x32x16_bf16 v[16:31], v[156:159], v[214:217], v[16:31]
	v_exp_f32_e32 v56, v56
	v_mfma_f32_32x32x16_bf16 v[0:15], v[152:155], v[214:217], v[0:15]
	v_exp_f32_e32 v57, v57
	v_exp_f32_e32 v58, v58
	v_exp_f32_e32 v59, v59
	v_exp_f32_e32 v60, v60
	v_exp_f32_e32 v61, v61
	v_exp_f32_e32 v62, v62
	v_exp_f32_e32 v63, v63
	v_cvt_pk_bf16_f32 v152, v56, v57
	v_cvt_pk_bf16_f32 v153, v58, v59
	v_cvt_pk_bf16_f32 v154, v60, v61
	v_cvt_pk_bf16_f32 v155, v62, v63
	s_waitcnt lgkmcnt(5)
	s_nop 0
	v_mfma_f32_32x32x16_bf16 v[16:31], v[148:151], v[152:155], v[16:31]
	v_exp_f32_e32 v32, v32
	s_waitcnt lgkmcnt(4)
	v_mfma_f32_32x32x16_bf16 v[0:15], v[144:147], v[152:155], v[0:15]
	v_exp_f32_e32 v33, v33
	v_exp_f32_e32 v34, v34
	v_exp_f32_e32 v35, v35
	v_exp_f32_e32 v36, v36
	v_exp_f32_e32 v37, v37
	v_exp_f32_e32 v38, v38
	v_exp_f32_e32 v39, v39
	v_cvt_pk_bf16_f32 v144, v32, v33
	v_cvt_pk_bf16_f32 v145, v34, v35
	v_cvt_pk_bf16_f32 v146, v36, v37
	v_cvt_pk_bf16_f32 v147, v38, v39
	s_waitcnt lgkmcnt(3)
	s_nop 0
	v_mfma_f32_32x32x16_bf16 v[16:31], v[140:143], v[144:147], v[16:31]
	v_exp_f32_e32 v40, v40
	s_waitcnt lgkmcnt(2)
	v_mfma_f32_32x32x16_bf16 v[0:15], v[136:139], v[144:147], v[0:15]
	v_exp_f32_e32 v41, v41
	v_exp_f32_e32 v42, v42
	v_exp_f32_e32 v43, v43
	v_exp_f32_e32 v44, v44
	v_exp_f32_e32 v45, v45
	v_exp_f32_e32 v46, v46
	v_exp_f32_e32 v47, v47
	v_cvt_pk_bf16_f32 v136, v40, v41
	v_cvt_pk_bf16_f32 v137, v42, v43
	v_cvt_pk_bf16_f32 v138, v44, v45
	v_cvt_pk_bf16_f32 v139, v46, v47
	s_andn2_b64 vcc, exec, s[36:37]
	s_waitcnt lgkmcnt(1)
	v_mfma_f32_32x32x16_bf16 v[16:31], v[132:135], v[136:139], v[16:31]
	s_waitcnt lgkmcnt(0)
	v_mfma_f32_32x32x16_bf16 v[0:15], v[128:131], v[136:139], v[0:15]
	s_cbranch_vccnz .Lsc0_c3_LBB0_809
	s_waitcnt vmcnt(5)
	ds_write_b128 v194, v[76:79]
	ds_write_b128 v204, v[80:83]
	ds_write_b128 v206, v[84:87]
	ds_write_b64 v208, v[92:93] offset:0
	ds_write_b64 v208, v[94:95] offset:16
	ds_write_b64 v208, v[104:105] offset:8704
	ds_write_b64 v208, v[106:107] offset:8720
